# v105 + non-temporal stores for the SwiGLU output F (369 MB, larger than the last-level cache)
# speedup vs baseline: 1.0180x; 1.0102x over previous
; __device__ __forceinline__ unsigned cvtpk(float lo, float hi) { f32x2_t v = {lo, hi}; bf16x2_t b = __builtin_convertvector(v, bf16x2_t); return __builtin_bit_cast(unsigned, b); }
; __device__ __forceinline__ float ex2(float v) { return __builtin_amdgcn_exp2f(v); }
; template <int mode>
; __device__ __forceinline__ void epilogue(f32x4 (&acc)[2][2][4][2], const GUnit& u, int wr, int wc, int fr, int fq, LAS unsigned char* lds) {
;     ...
;     } else {
;         bf16_t* base = (bf16_t*)u.C;
; #pragma unroll
;         for (int ai = 0; ai < 2; ++ai)
; #pragma unroll
;             for (int m = 0; m < 4; ++m) {
;                 bf16_t* rowp = base + (size_t)ai * u.SA + (size_t)(wr * 64 + m * 16 + fr) * u.SR + (wc >> 1) * u.SX + (wc & 1) * 32 + 8 * fq;
;                 float y[8];
; #pragma unroll
;                 for (int n = 0; n < 2; ++n)
; #pragma unroll
;                     for (int j = 0; j < 4; ++j) {
;                         const float g = acc[ai][0][m][n][j], up = acc[ai][1][m][n][j];
;                         y[n * 4 + j] = g * __builtin_amdgcn_rcpf(1.0f + ex2(-g * LOG2E)) * up;
;                     }
;                 u32x4 w; w.x = cvtpk(y[0], y[1]); w.y = cvtpk(y[2], y[3]); w.z = cvtpk(y[4], y[5]); w.w = cvtpk(y[6], y[7]);
;                 *(u32x4*)rowp = w;
;             }
.LBB0_823:
	v_mul_f32_e32 v156, 0xbfb8aa3b, v124
	v_exp_f32_e32 v158, v156
	v_mul_f32_e32 v156, 0xbfb8aa3b, v125
	v_exp_f32_e32 v159, v156
	v_lshl_add_u64 v[156:157], s[38:39], 0, v[144:145]
	v_add_f32_e32 v158, 1.0, v158
	v_rcp_f32_e32 v158, v158
	v_add_f32_e32 v159, 1.0, v159
	v_rcp_f32_e32 v159, v159
	v_lshl_add_u64 v[156:157], v[156:157], 0, s[6:7]
	s_mov_b32 s17, s7
	v_lshl_add_u64 v[156:157], v[156:157], 0, s[16:17]
	v_pk_mul_f32 v[124:125], v[124:125], v[158:159]
	v_mul_f32_e32 v158, 0xbfb8aa3b, v126
	v_mul_f32_e32 v159, 0xbfb8aa3b, v127
	v_exp_f32_e32 v158, v158
	v_exp_f32_e32 v159, v159
	v_pk_mul_f32 v[116:117], v[124:125], v[116:117]
	s_mov_b64 s[24:25], -1
	v_add_f32_e32 v124, 1.0, v158
	v_add_f32_e32 v125, 1.0, v159
	v_mul_f32_e32 v158, 0xbfb8aa3b, v120
	v_mul_f32_e32 v159, 0xbfb8aa3b, v121
	v_rcp_f32_e32 v124, v124
	v_rcp_f32_e32 v125, v125
	v_exp_f32_e32 v158, v158
	v_exp_f32_e32 v159, v159
	v_pk_mul_f32 v[124:125], v[126:127], v[124:125]
	v_add_f32_e32 v126, 1.0, v158
	v_add_f32_e32 v127, 1.0, v159
	v_mul_f32_e32 v158, 0xbfb8aa3b, v122
	v_mul_f32_e32 v159, 0xbfb8aa3b, v123
	v_exp_f32_e32 v158, v158
	v_exp_f32_e32 v159, v159
	v_rcp_f32_e32 v126, v126
	v_rcp_f32_e32 v127, v127
	v_add_f32_e32 v158, 1.0, v158
	v_add_f32_e32 v159, 1.0, v159
	v_rcp_f32_e32 v158, v158
	v_rcp_f32_e32 v159, v159
	v_pk_mul_f32 v[120:121], v[120:121], v[126:127]
	v_pk_mul_f32 v[118:119], v[124:125], v[118:119]
	v_pk_mul_f32 v[120:121], v[120:121], v[112:113]
	v_pk_mul_f32 v[112:113], v[122:123], v[158:159]
	v_lshl_add_u64 v[124:125], v[156:157], 0, v[138:139]
	v_pk_mul_f32 v[122:123], v[112:113], v[114:115]
	v_cvt_pk_bf16_f32 v112, v116, v117
	v_mul_f32_e32 v116, 0xbfb8aa3b, v108
	v_mul_f32_e32 v117, 0xbfb8aa3b, v109
	v_exp_f32_e32 v116, v116
	v_exp_f32_e32 v117, v117
	v_cvt_pk_bf16_f32 v113, v118, v119
	v_cvt_pk_bf16_f32 v114, v120, v121
	v_cvt_pk_bf16_f32 v115, v122, v123
	global_store_dwordx4 v[124:125], v[112:115], off nt
	s_nop 1
	v_add_f32_e32 v112, 1.0, v116
	v_add_f32_e32 v113, 1.0, v117
	v_rcp_f32_e32 v112, v112
	v_rcp_f32_e32 v113, v113
	v_lshl_add_u64 v[114:115], s[38:39], 0, v[146:147]
	v_lshl_add_u64 v[114:115], v[114:115], 0, s[6:7]
	v_lshl_add_u64 v[114:115], v[114:115], 0, s[16:17]
	v_pk_mul_f32 v[108:109], v[108:109], v[112:113]
	v_mul_f32_e32 v112, 0xbfb8aa3b, v110
	v_mul_f32_e32 v113, 0xbfb8aa3b, v111
	v_exp_f32_e32 v112, v112
	v_exp_f32_e32 v113, v113
	v_pk_mul_f32 v[100:101], v[108:109], v[100:101]
	v_add_f32_e32 v108, 1.0, v112
	v_add_f32_e32 v109, 1.0, v113
	v_mul_f32_e32 v112, 0xbfb8aa3b, v104
	v_mul_f32_e32 v113, 0xbfb8aa3b, v105
	v_rcp_f32_e32 v108, v108
	v_rcp_f32_e32 v109, v109
	v_exp_f32_e32 v112, v112
	v_exp_f32_e32 v113, v113
	v_pk_mul_f32 v[108:109], v[110:111], v[108:109]
	v_add_f32_e32 v110, 1.0, v112
	v_add_f32_e32 v111, 1.0, v113
	v_mul_f32_e32 v112, 0xbfb8aa3b, v106
	v_mul_f32_e32 v113, 0xbfb8aa3b, v107
	v_exp_f32_e32 v112, v112
	v_exp_f32_e32 v113, v113
	v_rcp_f32_e32 v110, v110
	v_rcp_f32_e32 v111, v111
	v_add_f32_e32 v112, 1.0, v112
	v_add_f32_e32 v113, 1.0, v113
	v_rcp_f32_e32 v112, v112
	v_rcp_f32_e32 v113, v113
	v_pk_mul_f32 v[104:105], v[104:105], v[110:111]
	v_pk_mul_f32 v[102:103], v[108:109], v[102:103]
	v_pk_mul_f32 v[104:105], v[104:105], v[96:97]
	v_pk_mul_f32 v[96:97], v[106:107], v[112:113]
	v_lshl_add_u64 v[108:109], v[114:115], 0, v[138:139]
	v_pk_mul_f32 v[106:107], v[96:97], v[98:99]
	v_cvt_pk_bf16_f32 v96, v100, v101
	v_mul_f32_e32 v100, 0xbfb8aa3b, v92
	v_mul_f32_e32 v101, 0xbfb8aa3b, v93
	v_exp_f32_e32 v100, v100
	v_exp_f32_e32 v101, v101
	v_cvt_pk_bf16_f32 v97, v102, v103
	v_cvt_pk_bf16_f32 v98, v104, v105
	v_cvt_pk_bf16_f32 v99, v106, v107
	global_store_dwordx4 v[108:109], v[96:99], off nt
	s_nop 1
	v_add_f32_e32 v96, 1.0, v100
	v_add_f32_e32 v97, 1.0, v101
	v_rcp_f32_e32 v96, v96
	v_rcp_f32_e32 v97, v97
	v_lshl_add_u64 v[98:99], s[38:39], 0, v[148:149]
	v_lshl_add_u64 v[98:99], v[98:99], 0, s[6:7]
	v_lshl_add_u64 v[98:99], v[98:99], 0, s[16:17]
	v_pk_mul_f32 v[92:93], v[92:93], v[96:97]
	v_mul_f32_e32 v96, 0xbfb8aa3b, v94
	v_mul_f32_e32 v97, 0xbfb8aa3b, v95
	v_exp_f32_e32 v96, v96
	v_exp_f32_e32 v97, v97
	v_pk_mul_f32 v[84:85], v[92:93], v[84:85]
	v_add_f32_e32 v92, 1.0, v96
	v_add_f32_e32 v93, 1.0, v97
	v_mul_f32_e32 v96, 0xbfb8aa3b, v88
	v_mul_f32_e32 v97, 0xbfb8aa3b, v89
	v_rcp_f32_e32 v92, v92
	v_rcp_f32_e32 v93, v93
	v_exp_f32_e32 v96, v96
	v_exp_f32_e32 v97, v97
	v_pk_mul_f32 v[92:93], v[94:95], v[92:93]
	v_add_f32_e32 v94, 1.0, v96
	v_add_f32_e32 v95, 1.0, v97
	v_mul_f32_e32 v96, 0xbfb8aa3b, v90
	v_mul_f32_e32 v97, 0xbfb8aa3b, v91
	v_exp_f32_e32 v96, v96
	v_exp_f32_e32 v97, v97
	v_rcp_f32_e32 v94, v94
	v_rcp_f32_e32 v95, v95
	v_add_f32_e32 v96, 1.0, v96
	v_add_f32_e32 v97, 1.0, v97
	v_rcp_f32_e32 v96, v96
	v_rcp_f32_e32 v97, v97
	v_pk_mul_f32 v[88:89], v[88:89], v[94:95]
	v_pk_mul_f32 v[86:87], v[92:93], v[86:87]
	v_pk_mul_f32 v[88:89], v[88:89], v[80:81]
	v_pk_mul_f32 v[80:81], v[90:91], v[96:97]
	v_lshl_add_u64 v[92:93], v[98:99], 0, v[138:139]
	v_pk_mul_f32 v[90:91], v[80:81], v[82:83]
	v_cvt_pk_bf16_f32 v80, v84, v85
	v_mul_f32_e32 v84, 0xbfb8aa3b, v76
	v_mul_f32_e32 v85, 0xbfb8aa3b, v77
	v_exp_f32_e32 v84, v84
	v_exp_f32_e32 v85, v85
	v_cvt_pk_bf16_f32 v81, v86, v87
	v_cvt_pk_bf16_f32 v82, v88, v89
	v_cvt_pk_bf16_f32 v83, v90, v91
	global_store_dwordx4 v[92:93], v[80:83], off nt
	s_nop 1
	v_add_f32_e32 v80, 1.0, v84
	v_add_f32_e32 v81, 1.0, v85
	v_rcp_f32_e32 v80, v80
	v_rcp_f32_e32 v81, v81
	v_lshl_add_u64 v[82:83], s[38:39], 0, v[150:151]
	v_lshl_add_u64 v[82:83], v[82:83], 0, s[6:7]
	v_lshl_add_u64 v[82:83], v[82:83], 0, s[16:17]
	v_pk_mul_f32 v[76:77], v[76:77], v[80:81]
; __device__ __forceinline__ unsigned cvtpk(float lo, float hi) { f32x2_t v = {lo, hi}; bf16x2_t b = __builtin_convertvector(v, bf16x2_t); return __builtin_bit_cast(unsigned, b); }
; __device__ __forceinline__ float ex2(float v) { return __builtin_amdgcn_exp2f(v); }
; template <int mode>
; __device__ __forceinline__ void epilogue(f32x4 (&acc)[2][2][4][2], const GUnit& u, int wr, int wc, int fr, int fq, LAS unsigned char* lds) {
;     ...
;     } else {
;         bf16_t* base = (bf16_t*)u.C;
; #pragma unroll
;         for (int ai = 0; ai < 2; ++ai)
; #pragma unroll
;             for (int m = 0; m < 4; ++m) {
;                 bf16_t* rowp = base + (size_t)ai * u.SA + (size_t)(wr * 64 + m * 16 + fr) * u.SR + (wc >> 1) * u.SX + (wc & 1) * 32 + 8 * fq;
;                 float y[8];
; #pragma unroll
;                 for (int n = 0; n < 2; ++n)
; #pragma unroll
;                     for (int j = 0; j < 4; ++j) {
;                         const float g = acc[ai][0][m][n][j], up = acc[ai][1][m][n][j];
;                         y[n * 4 + j] = g * __builtin_amdgcn_rcpf(1.0f + ex2(-g * LOG2E)) * up;
;                     }
;                 u32x4 w; w.x = cvtpk(y[0], y[1]); w.y = cvtpk(y[2], y[3]); w.z = cvtpk(y[4], y[5]); w.w = cvtpk(y[6], y[7]);
;                 *(u32x4*)rowp = w;
;             }
	v_mul_f32_e32 v80, 0xbfb8aa3b, v78
	v_mul_f32_e32 v81, 0xbfb8aa3b, v79
	v_exp_f32_e32 v80, v80
	v_exp_f32_e32 v81, v81
	v_pk_mul_f32 v[68:69], v[76:77], v[68:69]
	s_add_u32 s38, s38, 0x160000
	v_add_f32_e32 v76, 1.0, v80
	v_add_f32_e32 v77, 1.0, v81
	v_mul_f32_e32 v80, 0xbfb8aa3b, v72
	v_mul_f32_e32 v81, 0xbfb8aa3b, v73
	v_rcp_f32_e32 v76, v76
	v_rcp_f32_e32 v77, v77
	v_exp_f32_e32 v80, v80
	v_exp_f32_e32 v81, v81
	s_addc_u32 s39, s39, 0
	v_pk_mul_f32 v[76:77], v[78:79], v[76:77]
	v_add_f32_e32 v78, 1.0, v80
	v_add_f32_e32 v79, 1.0, v81
	v_mul_f32_e32 v80, 0xbfb8aa3b, v74
	v_mul_f32_e32 v81, 0xbfb8aa3b, v75
	v_exp_f32_e32 v80, v80
	v_exp_f32_e32 v81, v81
	v_rcp_f32_e32 v78, v78
	v_rcp_f32_e32 v79, v79
	v_add_f32_e32 v80, 1.0, v80
	v_add_f32_e32 v81, 1.0, v81
	v_rcp_f32_e32 v80, v80
	v_rcp_f32_e32 v81, v81
	v_pk_mul_f32 v[72:73], v[72:73], v[78:79]
	v_pk_mul_f32 v[70:71], v[76:77], v[70:71]
	v_pk_mul_f32 v[72:73], v[72:73], v[64:65]
	v_pk_mul_f32 v[64:65], v[74:75], v[80:81]
	v_lshl_add_u64 v[76:77], v[82:83], 0, v[138:139]
	v_pk_mul_f32 v[74:75], v[64:65], v[66:67]
	v_cvt_pk_bf16_f32 v64, v68, v69
	v_cvt_pk_bf16_f32 v65, v70, v71
	v_cvt_pk_bf16_f32 v66, v72, v73
	v_cvt_pk_bf16_f32 v67, v74, v75
	global_store_dwordx4 v[76:77], v[64:67], off nt
	s_andn2_b64 vcc, exec, s[36:37]
	s_nop 0
	v_mul_f32_e32 v64, 0xbfb8aa3b, v60
	v_mul_f32_e32 v65, 0xbfb8aa3b, v61
	v_exp_f32_e32 v64, v64
	v_exp_f32_e32 v65, v65
	v_lshl_add_u64 v[66:67], s[38:39], 0, v[144:145]
	v_lshl_add_u64 v[66:67], v[66:67], 0, s[6:7]
	v_add_f32_e32 v64, 1.0, v64
	v_add_f32_e32 v65, 1.0, v65
	v_rcp_f32_e32 v64, v64
	v_rcp_f32_e32 v65, v65
	v_lshl_add_u64 v[66:67], v[66:67], 0, s[16:17]
	v_pk_mul_f32 v[60:61], v[60:61], v[64:65]
	v_mul_f32_e32 v64, 0xbfb8aa3b, v62
	v_mul_f32_e32 v65, 0xbfb8aa3b, v63
	v_exp_f32_e32 v64, v64
	v_exp_f32_e32 v65, v65
	v_pk_mul_f32 v[52:53], v[60:61], v[52:53]
	v_add_f32_e32 v60, 1.0, v64
	v_add_f32_e32 v61, 1.0, v65
	v_mul_f32_e32 v64, 0xbfb8aa3b, v56
	v_mul_f32_e32 v65, 0xbfb8aa3b, v57
	v_rcp_f32_e32 v60, v60
	v_rcp_f32_e32 v61, v61
	v_exp_f32_e32 v64, v64
	v_exp_f32_e32 v65, v65
	v_pk_mul_f32 v[60:61], v[62:63], v[60:61]
	v_add_f32_e32 v62, 1.0, v64
	v_add_f32_e32 v63, 1.0, v65
	v_mul_f32_e32 v64, 0xbfb8aa3b, v58
	v_mul_f32_e32 v65, 0xbfb8aa3b, v59
	v_exp_f32_e32 v64, v64
	v_exp_f32_e32 v65, v65
	v_rcp_f32_e32 v62, v62
	v_rcp_f32_e32 v63, v63
	v_add_f32_e32 v64, 1.0, v64
	v_add_f32_e32 v65, 1.0, v65
	v_rcp_f32_e32 v64, v64
	v_rcp_f32_e32 v65, v65
	v_pk_mul_f32 v[56:57], v[56:57], v[62:63]
	v_pk_mul_f32 v[54:55], v[60:61], v[54:55]
	v_pk_mul_f32 v[56:57], v[56:57], v[48:49]
	v_pk_mul_f32 v[48:49], v[58:59], v[64:65]
	v_lshl_add_u64 v[60:61], v[66:67], 0, v[138:139]
	v_pk_mul_f32 v[58:59], v[48:49], v[50:51]
	v_cvt_pk_bf16_f32 v48, v52, v53
	v_mul_f32_e32 v52, 0xbfb8aa3b, v44
	v_mul_f32_e32 v53, 0xbfb8aa3b, v45
	v_exp_f32_e32 v52, v52
	v_exp_f32_e32 v53, v53
	v_cvt_pk_bf16_f32 v49, v54, v55
	v_cvt_pk_bf16_f32 v50, v56, v57
	v_cvt_pk_bf16_f32 v51, v58, v59
	global_store_dwordx4 v[60:61], v[48:51], off nt
	s_nop 1
	v_add_f32_e32 v48, 1.0, v52
	v_add_f32_e32 v49, 1.0, v53
	v_rcp_f32_e32 v48, v48
	v_rcp_f32_e32 v49, v49
	v_lshl_add_u64 v[50:51], s[38:39], 0, v[146:147]
	v_lshl_add_u64 v[50:51], v[50:51], 0, s[6:7]
	v_lshl_add_u64 v[50:51], v[50:51], 0, s[16:17]
	v_pk_mul_f32 v[44:45], v[44:45], v[48:49]
	v_mul_f32_e32 v48, 0xbfb8aa3b, v46
	v_mul_f32_e32 v49, 0xbfb8aa3b, v47
	v_exp_f32_e32 v48, v48
	v_exp_f32_e32 v49, v49
	v_pk_mul_f32 v[36:37], v[44:45], v[36:37]
	v_add_f32_e32 v44, 1.0, v48
	v_add_f32_e32 v45, 1.0, v49
	v_mul_f32_e32 v48, 0xbfb8aa3b, v40
	v_mul_f32_e32 v49, 0xbfb8aa3b, v41
	v_rcp_f32_e32 v44, v44
	v_rcp_f32_e32 v45, v45
	v_exp_f32_e32 v48, v48
	v_exp_f32_e32 v49, v49
	v_pk_mul_f32 v[44:45], v[46:47], v[44:45]
	v_add_f32_e32 v46, 1.0, v48
	v_add_f32_e32 v47, 1.0, v49
	v_mul_f32_e32 v48, 0xbfb8aa3b, v42
	v_mul_f32_e32 v49, 0xbfb8aa3b, v43
	v_exp_f32_e32 v48, v48
	v_exp_f32_e32 v49, v49
; __device__ __forceinline__ unsigned cvtpk(float lo, float hi) { f32x2_t v = {lo, hi}; bf16x2_t b = __builtin_convertvector(v, bf16x2_t); return __builtin_bit_cast(unsigned, b); }
; __device__ __forceinline__ float ex2(float v) { return __builtin_amdgcn_exp2f(v); }
; #define PG8_BAR __builtin_amdgcn_s_barrier()
; template <int mode>
; __device__ __forceinline__ void epilogue(f32x4 (&acc)[2][2][4][2], const GUnit& u, int wr, int wc, int fr, int fq, LAS unsigned char* lds) {
;     ...
;     } else {
;         bf16_t* base = (bf16_t*)u.C;
; #pragma unroll
;         for (int ai = 0; ai < 2; ++ai)
; #pragma unroll
;             for (int m = 0; m < 4; ++m) {
;                 bf16_t* rowp = base + (size_t)ai * u.SA + (size_t)(wr * 64 + m * 16 + fr) * u.SR + (wc >> 1) * u.SX + (wc & 1) * 32 + 8 * fq;
;                 float y[8];
; #pragma unroll
;                 for (int n = 0; n < 2; ++n)
; #pragma unroll
;                     for (int j = 0; j < 4; ++j) {
;                         const float g = acc[ai][0][m][n][j], up = acc[ai][1][m][n][j];
;                         y[n * 4 + j] = g * __builtin_amdgcn_rcpf(1.0f + ex2(-g * LOG2E)) * up;
;                     }
;                 u32x4 w; w.x = cvtpk(y[0], y[1]); w.y = cvtpk(y[2], y[3]); w.z = cvtpk(y[4], y[5]); w.w = cvtpk(y[6], y[7]);
;                 *(u32x4*)rowp = w;
;             }
; template <int GI>
; __device__ __forceinline__ void gemm_phase(LAS unsigned char* lds, unsigned char* ws, int G, int cblk) {
;     ...
;         if (wr == 0) PG8_BAR;
;         epilogue<g.mode>(acc, cur, wr, wc, fr, fq, lds);
;         if (!has_next) break;
; #pragma unroll
;         for (int a = 0; a < 2; ++a)
; #pragma unroll
;             for (int b = 0; b < 2; ++b)
; #pragma unroll
;                 for (int m = 0; m < 4; ++m)
; #pragma unroll
;                     for (int n = 0; n < 2; ++n) acc[a][b][m][n] = (f32x4){0.f, 0.f, 0.f, 0.f};
;         cur = nxt; cA = nA; cB = nB; ++ui;
;         if (wr == 1) PG8_BAR;
	v_rcp_f32_e32 v46, v46
	v_rcp_f32_e32 v47, v47
	v_add_f32_e32 v48, 1.0, v48
	v_add_f32_e32 v49, 1.0, v49
	v_rcp_f32_e32 v48, v48
	v_rcp_f32_e32 v49, v49
	v_pk_mul_f32 v[40:41], v[40:41], v[46:47]
	v_pk_mul_f32 v[38:39], v[44:45], v[38:39]
	v_pk_mul_f32 v[40:41], v[40:41], v[32:33]
	v_pk_mul_f32 v[32:33], v[42:43], v[48:49]
	v_lshl_add_u64 v[44:45], v[50:51], 0, v[138:139]
	v_pk_mul_f32 v[42:43], v[32:33], v[34:35]
	v_cvt_pk_bf16_f32 v32, v36, v37
	v_mul_f32_e32 v36, 0xbfb8aa3b, v28
	v_mul_f32_e32 v37, 0xbfb8aa3b, v29
	v_exp_f32_e32 v36, v36
	v_exp_f32_e32 v37, v37
	v_cvt_pk_bf16_f32 v33, v38, v39
	v_cvt_pk_bf16_f32 v34, v40, v41
	v_cvt_pk_bf16_f32 v35, v42, v43
	global_store_dwordx4 v[44:45], v[32:35], off nt
	s_nop 1
	v_add_f32_e32 v32, 1.0, v36
	v_add_f32_e32 v33, 1.0, v37
	v_rcp_f32_e32 v32, v32
	v_rcp_f32_e32 v33, v33
	v_lshl_add_u64 v[34:35], s[38:39], 0, v[148:149]
	v_lshl_add_u64 v[34:35], v[34:35], 0, s[6:7]
	v_lshl_add_u64 v[34:35], v[34:35], 0, s[16:17]
	v_pk_mul_f32 v[28:29], v[28:29], v[32:33]
	v_mul_f32_e32 v32, 0xbfb8aa3b, v30
	v_mul_f32_e32 v33, 0xbfb8aa3b, v31
	v_exp_f32_e32 v32, v32
	v_exp_f32_e32 v33, v33
	v_pk_mul_f32 v[20:21], v[28:29], v[20:21]
	v_add_f32_e32 v28, 1.0, v32
	v_add_f32_e32 v29, 1.0, v33
	v_mul_f32_e32 v32, 0xbfb8aa3b, v24
	v_mul_f32_e32 v33, 0xbfb8aa3b, v25
	v_rcp_f32_e32 v28, v28
	v_rcp_f32_e32 v29, v29
	v_exp_f32_e32 v32, v32
	v_exp_f32_e32 v33, v33
	v_pk_mul_f32 v[28:29], v[30:31], v[28:29]
	v_add_f32_e32 v30, 1.0, v32
	v_add_f32_e32 v31, 1.0, v33
	v_mul_f32_e32 v32, 0xbfb8aa3b, v26
	v_mul_f32_e32 v33, 0xbfb8aa3b, v27
	v_exp_f32_e32 v32, v32
	v_exp_f32_e32 v33, v33
	v_rcp_f32_e32 v30, v30
	v_rcp_f32_e32 v31, v31
	v_add_f32_e32 v32, 1.0, v32
	v_add_f32_e32 v33, 1.0, v33
	v_rcp_f32_e32 v32, v32
	v_rcp_f32_e32 v33, v33
	v_pk_mul_f32 v[24:25], v[24:25], v[30:31]
	v_pk_mul_f32 v[22:23], v[28:29], v[22:23]
	v_pk_mul_f32 v[24:25], v[24:25], v[16:17]
	v_pk_mul_f32 v[16:17], v[26:27], v[32:33]
	v_lshl_add_u64 v[28:29], v[34:35], 0, v[138:139]
	v_pk_mul_f32 v[26:27], v[16:17], v[18:19]
	v_cvt_pk_bf16_f32 v16, v20, v21
	v_mul_f32_e32 v20, 0xbfb8aa3b, v12
	v_mul_f32_e32 v21, 0xbfb8aa3b, v13
	v_exp_f32_e32 v20, v20
	v_exp_f32_e32 v21, v21
	v_cvt_pk_bf16_f32 v17, v22, v23
	v_cvt_pk_bf16_f32 v18, v24, v25
	v_cvt_pk_bf16_f32 v19, v26, v27
	global_store_dwordx4 v[28:29], v[16:19], off nt
	s_nop 1
	v_add_f32_e32 v16, 1.0, v20
	v_add_f32_e32 v17, 1.0, v21
	v_rcp_f32_e32 v16, v16
	v_rcp_f32_e32 v17, v17
	v_lshl_add_u64 v[18:19], s[38:39], 0, v[150:151]
	v_lshl_add_u64 v[18:19], v[18:19], 0, s[6:7]
	v_lshl_add_u64 v[18:19], v[18:19], 0, s[16:17]
	v_pk_mul_f32 v[12:13], v[12:13], v[16:17]
	v_mul_f32_e32 v16, 0xbfb8aa3b, v14
	v_mul_f32_e32 v17, 0xbfb8aa3b, v15
	v_exp_f32_e32 v16, v16
	v_exp_f32_e32 v17, v17
	v_pk_mul_f32 v[4:5], v[12:13], v[4:5]
	v_add_f32_e32 v12, 1.0, v16
	v_add_f32_e32 v13, 1.0, v17
	v_mul_f32_e32 v16, 0xbfb8aa3b, v8
	v_mul_f32_e32 v17, 0xbfb8aa3b, v9
	v_rcp_f32_e32 v12, v12
	v_rcp_f32_e32 v13, v13
	v_exp_f32_e32 v16, v16
	v_exp_f32_e32 v17, v17
	v_pk_mul_f32 v[12:13], v[14:15], v[12:13]
	v_add_f32_e32 v14, 1.0, v16
	v_add_f32_e32 v15, 1.0, v17
	v_mul_f32_e32 v16, 0xbfb8aa3b, v10
	v_mul_f32_e32 v17, 0xbfb8aa3b, v11
	v_exp_f32_e32 v16, v16
	v_exp_f32_e32 v17, v17
	v_rcp_f32_e32 v14, v14
	v_rcp_f32_e32 v15, v15
	v_add_f32_e32 v16, 1.0, v16
	v_add_f32_e32 v17, 1.0, v17
	v_rcp_f32_e32 v16, v16
	v_rcp_f32_e32 v17, v17
	v_pk_mul_f32 v[8:9], v[8:9], v[14:15]
	v_pk_mul_f32 v[6:7], v[12:13], v[6:7]
	v_pk_mul_f32 v[8:9], v[8:9], v[0:1]
	v_pk_mul_f32 v[0:1], v[10:11], v[16:17]
	v_lshl_add_u64 v[12:13], v[18:19], 0, v[138:139]
	v_pk_mul_f32 v[10:11], v[0:1], v[2:3]
	v_cvt_pk_bf16_f32 v0, v4, v5
	v_cvt_pk_bf16_f32 v1, v6, v7
	v_cvt_pk_bf16_f32 v2, v8, v9
	v_cvt_pk_bf16_f32 v3, v10, v11
	global_store_dwordx4 v[12:13], v[0:3], off nt
	s_cbranch_vccnz .LBB0_816
	s_andn2_b64 vcc, exec, s[8:9]
	s_cbranch_vccnz .LBB0_815
	s_barrier
	s_branch .LBB0_815
